# same instruction-fetch warming, with the read-ahead of the last three GEMM loops clamped so that it never reads past the end of the kernel's code
# speedup vs baseline: 1.0036x; 1.0036x over previous
.LBB0_1987:
	v_add_u32_e32 v2, s58, v199
	ds_read_b128 v[134:137], v2
	ds_read_b128 v[138:141], v2 offset:1024
	ds_read_b128 v[142:145], v2 offset:2048
	ds_read_b128 v[146:149], v2 offset:3072
	v_add_u32_e32 v2, s59, v199
	ds_read_b128 v[150:153], v2
	ds_read_b128 v[154:157], v2 offset:1024
	ds_read_b128 v[158:161], v2 offset:2048
	ds_read_b128 v[162:165], v2 offset:3072
	s_add_i32 s63, s40, 2
	s_add_u32 s64, s38, 0x80
	s_addc_u32 s41, s39, 0
	s_cmp_eq_u32 s57, s40
	s_cselect_b32 s40, s3, s64
	s_cselect_b32 s41, s1, s41
	s_cselect_b32 s65, s10, s62
	s_cselect_b32 s64, s27, s29
	s_cbranch_scc0 .Lpf_skip_4
	s_getpc_b64 s[98:99]
	s_mov_b32 m0, 0x22800
	v_lshlrev_b32_e32 v4, 7, v0
	v_min_u32_e32 v4, 0x8480, v4
	global_load_lds_dword v4, s[98:99]

.LBB0_2160:
	s_waitcnt lgkmcnt(0)
	ds_read_b128 v[130:133], v220
	ds_read_b128 v[134:137], v220 offset:1024
	ds_read_b128 v[138:141], v220 offset:2048
	ds_read_b128 v[142:145], v220 offset:3072
	ds_read_b128 v[146:149], v221
	ds_read_b128 v[150:153], v221 offset:1024
	ds_read_b128 v[154:157], v221 offset:2048
	ds_read_b128 v[158:161], v221 offset:3072
	s_add_i32 s62, s42, 2
	s_add_u32 s63, s40, 0x80
	s_addc_u32 s43, s41, 0
	s_cmp_eq_u32 s54, s42
	s_cselect_b32 s42, s29, s63
	s_cselect_b32 s43, s13, s43
	s_cselect_b32 s65, s31, s61
	s_cselect_b32 s64, s59, s60
	s_cbranch_scc0 .Lpf_skip_5
	s_getpc_b64 s[98:99]
	s_mov_b32 m0, 0x22800
	v_lshlrev_b32_e32 v214, 7, v0
	v_min_u32_e32 v214, 0x4c80, v214
	global_load_lds_dword v214, s[98:99]

.LBB0_2194:
	v_add_u32_e32 v103, s53, v146
	ds_read_b128 v[148:151], v103
	ds_read_b128 v[152:155], v103 offset:1024
	ds_read_b128 v[156:159], v103 offset:2048
	ds_read_b128 v[160:163], v103 offset:3072
	v_add_u32_e32 v103, s54, v146
	ds_read_b128 v[164:167], v103
	ds_read_b128 v[168:171], v103 offset:1024
	ds_read_b128 v[172:175], v103 offset:2048
	ds_read_b128 v[176:179], v103 offset:3072
	s_add_i32 s63, s36, 2
	s_add_u32 s64, s34, 0x80
	s_addc_u32 s37, s35, 0
	s_cmp_eq_u32 s52, s36
	s_cselect_b32 s36, s23, s64
	s_cselect_b32 s37, s21, s37
	s_cselect_b32 s65, s59, s62
	s_cselect_b32 s64, s60, s61
	s_cbranch_scc0 .Lpf_skip_6
	s_getpc_b64 s[98:99]
	s_mov_b32 m0, 0x22800
	v_lshlrev_b32_e32 v104, 7, v0
	v_min_u32_e32 v104, 0x3000, v104
	global_load_lds_dword v104, s[98:99]
